# one static s_setprio 1 for waves 4-7 across the whole mixer (attention) phase, reset to 0 at its end
# speedup vs baseline: 1.0087x; 1.0002x over previous
; #define LAS __attribute__((address_space(3)))
; __device__ __forceinline__ void mixer_phase(const Args& a, LAS unsigned char* lds, int l, unsigned* ctr) {
;     ...
;     const int nC = 512, nA = 512, nCc = last ? 0 : 16, nAc = last ? 0 : 16, nB = last ? 1024 : 1056;
;     const int total = nC + nA + nCc + nAc + nB;
;     const float* lv = a.in[I_LAM] + l * 4 * 48;
;     float d1 = 0.f, d2 = 0.f;
;     for (int i = 0; i < 48; ++i) { d1 += lv[i] * lv[48 + i]; d2 += lv[96 + i] * lv[144 + i]; }
;     const float lam_init = 0.8f - 0.6f * expf(-0.3f * (float)l);
;     const float lam = expf(d1) - expf(d2) + lam_init;
;     LAS unsigned* sidx = (LAS unsigned*)(lds + LDS_MISC + 64);
.LBB0_576:
	s_add_u32 s6, s70, s0
	s_addc_u32 s7, s71, s1
	global_load_dwordx4 v[2:5], v195, s[6:7] offset:48
	global_load_dwordx4 v[6:9], v195, s[6:7] offset:32
	global_load_dwordx4 v[10:13], v195, s[6:7] offset:16
	global_load_dwordx4 v[14:17], v195, s[6:7]
	global_load_dwordx4 v[18:21], v195, s[6:7] offset:240
	global_load_dwordx4 v[22:25], v195, s[6:7] offset:224
	global_load_dwordx4 v[26:29], v195, s[6:7] offset:208
	global_load_dwordx4 v[30:33], v195, s[6:7] offset:192
	global_load_dwordx4 v[34:37], v195, s[6:7] offset:432
	global_load_dwordx4 v[38:41], v195, s[6:7] offset:416
	global_load_dwordx4 v[42:45], v195, s[6:7] offset:400
	global_load_dwordx4 v[46:49], v195, s[6:7] offset:384
	global_load_dwordx4 v[50:53], v195, s[6:7] offset:624
	global_load_dwordx4 v[54:57], v195, s[6:7] offset:608
	global_load_dwordx4 v[58:61], v195, s[6:7] offset:592
	global_load_dwordx4 v[62:65], v195, s[6:7] offset:576
	s_add_u32 s0, s0, 64
	s_addc_u32 s1, s1, 0
	s_cmpk_eq_i32 s0, 0xc0
	s_waitcnt vmcnt(12)
	v_mov_b32_e32 v66, v14
	v_mov_b32_e32 v14, v16
	s_waitcnt vmcnt(9)
	v_mov_b32_e32 v16, v26
	s_waitcnt vmcnt(8)
	v_mov_b32_e32 v68, v30
	v_mov_b32_e32 v30, v32
	s_waitcnt vmcnt(4)
	v_mov_b32_e32 v67, v46
	v_mov_b32_e32 v46, v15
	v_mov_b32_e32 v15, v48
	v_mov_b32_e32 v48, v17
	s_waitcnt vmcnt(0)
	v_mov_b32_e32 v69, v62
	v_fma_f32 v0, v66, v68, v0
	v_fma_f32 v1, v67, v69, v1
	v_mov_b32_e32 v62, v31
	v_fma_f32 v0, v46, v62, v0
	v_fma_f32 v1, v47, v63, v1
	v_mov_b32_e32 v31, v64
	v_fma_f32 v0, v14, v30, v0
	v_fma_f32 v1, v15, v31, v1
	v_mov_b32_e32 v64, v33
	v_fma_f32 v0, v48, v64, v0
	v_fma_f32 v1, v49, v65, v1
	v_mov_b32_e32 v14, v10
	v_mov_b32_e32 v15, v42
	v_mov_b32_e32 v17, v58
	v_fma_f32 v0, v14, v16, v0
	v_fma_f32 v1, v15, v17, v1
	v_mov_b32_e32 v42, v11
	v_mov_b32_e32 v58, v27
	v_fma_f32 v0, v42, v58, v0
	v_fma_f32 v1, v43, v59, v1
	v_mov_b32_e32 v10, v12
	v_mov_b32_e32 v11, v44
	v_mov_b32_e32 v14, v28
	v_mov_b32_e32 v15, v60
	v_fma_f32 v0, v10, v14, v0
	v_fma_f32 v1, v11, v15, v1
	v_mov_b32_e32 v44, v13
	v_mov_b32_e32 v60, v29
	v_fma_f32 v0, v44, v60, v0
	v_fma_f32 v1, v45, v61, v1
	v_mov_b32_e32 v10, v6
	v_mov_b32_e32 v11, v38
	v_mov_b32_e32 v12, v22
	v_mov_b32_e32 v13, v54
	v_fma_f32 v0, v10, v12, v0
	v_fma_f32 v1, v11, v13, v1
	v_mov_b32_e32 v38, v7
	v_mov_b32_e32 v54, v23
	v_fma_f32 v0, v38, v54, v0
	v_fma_f32 v1, v39, v55, v1
	v_mov_b32_e32 v6, v8
	v_mov_b32_e32 v7, v40
	v_mov_b32_e32 v10, v24
	v_mov_b32_e32 v11, v56
	v_fma_f32 v0, v6, v10, v0
	v_fma_f32 v1, v7, v11, v1
	v_mov_b32_e32 v40, v9
	v_mov_b32_e32 v56, v25
	v_fma_f32 v0, v40, v56, v0
	v_fma_f32 v1, v41, v57, v1
	v_mov_b32_e32 v6, v2
	v_mov_b32_e32 v7, v34
	v_mov_b32_e32 v8, v18
	v_mov_b32_e32 v9, v50
	v_fma_f32 v0, v6, v8, v0
	v_fma_f32 v1, v7, v9, v1
	v_mov_b32_e32 v34, v3
	v_mov_b32_e32 v50, v19
	v_fma_f32 v0, v34, v50, v0
	v_fma_f32 v1, v35, v51, v1
	v_mov_b32_e32 v2, v4
	v_mov_b32_e32 v3, v36
	v_mov_b32_e32 v6, v20
	v_mov_b32_e32 v7, v52
	v_fma_f32 v0, v2, v6, v0
	v_fma_f32 v1, v3, v7, v1
	v_mov_b32_e32 v36, v5
	v_mov_b32_e32 v52, v21
	v_fma_f32 v0, v36, v52, v0
	v_fma_f32 v1, v37, v53, v1
	s_cbranch_scc0 .LBB0_576
	v_readlane_b32 s6, v255, 20
	s_lshl_b32 s22, s6, 6
	s_lshl_b64 s[0:1], s[22:23], 2
	v_readlane_b32 s5, v252, 51
	s_add_u32 s78, s5, s0
	v_readlane_b32 s0, v252, 52
	s_addc_u32 s79, s0, s1
	s_cmp_eq_u32 s6, 3
	s_cselect_b64 s[0:1], -1, 0
	v_cvt_f32_u32_e32 v2, s6
	v_writelane_b32 v255, s0, 25
	s_mov_b32 s5, 0x42b17218
	v_mov_b32_e32 v6, 0x7f800000
	v_writelane_b32 v255, s1, 26
	s_and_b64 s[0:1], s[0:1], exec
	s_cselect_b32 s1, 0, 16
	s_movk_i32 s0, 0x800
	s_cselect_b32 s0, s0, 0x820
	s_lshl_b32 s47, s1, 1
	v_mul_f32_e32 v2, 0xbe99999a, v2
	s_add_i32 s47, s47, s0
	v_mul_f32_e32 v3, 0x3fb8aa3b, v2
	s_mov_b32 s0, 0x3fb8aa3b
	v_fma_f32 v4, v2, s0, -v3
	v_rndne_f32_e32 v5, v3
	v_fmac_f32_e32 v4, 0x32a5705f, v2
	v_sub_f32_e32 v3, v3, v5
	v_add_f32_e32 v3, v3, v4
	v_exp_f32_e32 v3, v3
	v_cvt_i32_f32_e32 v4, v5
	s_mov_b32 s20, s1
	s_mov_b32 s1, 0xc2ce8ed0
	v_cmp_ngt_f32_e32 vcc, s1, v2
	v_ldexp_f32 v3, v3, v4
	v_readlane_b32 s48, v252, 0
	v_cndmask_b32_e32 v3, 0, v3, vcc
	v_cmp_nlt_f32_e32 vcc, s5, v2
	v_readlane_b32 s62, v252, 14
	v_readlane_b32 s63, v252, 15
	v_cndmask_b32_e32 v2, v6, v3, vcc
	v_mov_b32_e32 v3, 0x3f4ccccd
	v_fmamk_f32 v2, v2, 0xbf19999a, v3
	v_mul_f32_e32 v3, 0x3fb8aa3b, v0
	v_rndne_f32_e32 v4, v3
	v_sub_f32_e32 v5, v3, v4
	v_fma_f32 v3, v0, s0, -v3
	v_fmac_f32_e32 v3, 0x32a5705f, v0
	v_add_f32_e32 v3, v5, v3
	v_exp_f32_e32 v3, v3
	v_cvt_i32_f32_e32 v4, v4
	v_cmp_ngt_f32_e32 vcc, s1, v0
	s_mov_b64 s[12:13], s[68:69]
	s_lshl_b32 s22, s6, 8
	v_ldexp_f32 v3, v3, v4
	v_cndmask_b32_e32 v3, 0, v3, vcc
	v_cmp_nlt_f32_e32 vcc, s5, v0
	v_readlane_b32 s60, v252, 12
	v_readlane_b32 s61, v252, 13
	v_cndmask_b32_e32 v0, v6, v3, vcc
	v_mul_f32_e32 v3, 0x3fb8aa3b, v1
	v_rndne_f32_e32 v4, v3
	v_sub_f32_e32 v5, v3, v4
	v_fma_f32 v3, v1, s0, -v3
	v_fmac_f32_e32 v3, 0x32a5705f, v1
	v_add_f32_e32 v3, v5, v3
	v_exp_f32_e32 v3, v3
	v_cvt_i32_f32_e32 v4, v4
	v_cmp_ngt_f32_e32 vcc, s1, v1
	s_mov_b64 s[14:15], s[70:71]
	s_mov_b64 s[16:17], s[72:73]
	v_ldexp_f32 v3, v3, v4
	s_mov_b64 s[18:19], s[74:75]
	s_mov_b64 s[70:71], s[62:63]
	v_cndmask_b32_e32 v3, 0, v3, vcc
	v_cmp_nlt_f32_e32 vcc, s5, v1
	s_lshl_b32 s5, s6, 18
	s_lshl_b32 s0, s6, 9
	s_lshl_b64 s[8:9], s[22:23], 2
	s_mov_b64 s[68:69], s[60:61]
	s_add_u32 s26, s68, s8
	s_addc_u32 s27, s69, s9
	s_mov_b32 s1, s23
	s_add_u32 s8, s70, s5
	s_addc_u32 s9, s71, 0
	s_lshl_b64 s[0:1], s[0:1], 2
	v_writelane_b32 v255, s8, 27
	s_add_u32 s0, s12, s0
	s_addc_u32 s1, s13, s1
	v_writelane_b32 v255, s9, 28
	s_mulk_i32 s6, 0x60
	s_mov_b32 s7, s23
	v_writelane_b32 v255, s0, 29
	v_cndmask_b32_e32 v1, v6, v3, vcc
	v_readlane_b32 s49, v252, 1
	v_writelane_b32 v255, s1, 30
	s_lshl_b64 s[0:1], s[6:7], 2
	v_sub_f32_e32 v0, v0, v1
	v_readlane_b32 s50, v252, 2
	v_readlane_b32 s51, v252, 3
	v_readlane_b32 s52, v252, 4
	v_readlane_b32 s53, v252, 5
	v_readlane_b32 s54, v252, 6
	v_readlane_b32 s55, v252, 7
	s_add_u32 s80, s16, s0
	v_readlane_b32 s82, v252, 53
	v_readlane_b32 s48, v254, 21
	v_add_f32_e32 v216, v2, v0
	v_sub_f32_e32 v217, 1.0, v2
	s_addc_u32 s81, s17, s1
	v_readlane_b32 s83, v252, 54
	v_readlane_b32 s25, v255, 19
	v_readlane_b32 s49, v254, 22
	v_readlane_b32 s21, v254, 23
	v_readlane_b32 s24, v254, 24
	v_readlane_b32 s50, v254, 25
	v_readlane_b32 s51, v254, 26
	v_readlane_b32 s52, v254, 27
	v_readlane_b32 s53, v254, 28
	v_readlane_b32 s54, v254, 33
	v_readlane_b32 s55, v254, 34
	s_mov_b32 s60, 0x8400
	s_movk_i32 s61, 0x60
	s_movk_i32 s62, 0x100
	s_mov_b32 s63, 0x2aaaaaab
	v_readlane_b32 s75, v255, 17
	v_readlane_b32 s56, v252, 8
	v_readlane_b32 s57, v252, 9
	v_readlane_b32 s58, v252, 10
	v_readlane_b32 s59, v252, 11
	v_readfirstlane_b32 s98, v192
	s_cmpk_lt_u32 s98, 0x100
	s_cbranch_scc1 .Lmix_prio_skip
	s_setprio 1
.Lmix_prio_skip:
	s_branch .LBB0_581

; __device__ __forceinline__ int opaque_tid() { int t = threadIdx.x; asm volatile("" : "+v"(t)); return t; }
; __device__ __forceinline__ void xcd_barrier(const XcdBarrier& b) {
;     asm volatile("s_waitcnt vmcnt(0)" ::: "memory");
;     __syncthreads();
;     if (opaque_tid() == 0) {
;         unsigned* bar = b.bar;
;         __builtin_amdgcn_s_waitcnt(0);
;         unsigned nloc = b.st[0], nx = b.st[1];
;         if (nloc == 0u) { xcd_barrier_complete(bar, b.x, nloc, nx); b.st[0] = nloc; b.st[1] = nx; }
.LBB0_853:
	s_setprio 0
	s_waitcnt vmcnt(0)
	v_mov_b32_e32 v0, v192
	s_barrier
	s_nop 0
	v_cmp_eq_u32_e32 vcc, 0, v0
	s_mov_b64 s[0:1], exec
	v_readlane_b32 s48, v252, 18
	v_readlane_b32 s49, v252, 19
	v_readlane_b32 s50, v252, 20
	v_readlane_b32 s51, v252, 21
	v_readlane_b32 s52, v252, 22
	v_readlane_b32 s53, v252, 23
	v_readlane_b32 s54, v252, 24
	v_readlane_b32 s55, v252, 25
	v_readlane_b32 s56, v252, 26
	v_readlane_b32 s57, v252, 27
	v_readlane_b32 s60, v252, 30
	v_readlane_b32 s61, v252, 31
	v_readlane_b32 s62, v252, 32
	v_readlane_b32 s63, v252, 33
	s_mov_b64 s[36:37], s[48:49]
	s_mov_b64 s[38:39], s[50:51]
	s_mov_b64 s[40:41], s[52:53]
	s_mov_b64 s[42:43], s[54:55]
	v_readlane_b32 s34, v255, 7
	v_readlane_b32 s48, v255, 9
	v_readlane_b32 s50, v255, 11
	v_readlane_b32 s52, v255, 13
	v_readlane_b32 s54, v252, 59
	v_readlane_b32 s56, v252, 61
	v_readlane_b32 s60, v252, 63
	v_readlane_b32 s62, v253, 1
	v_readlane_b32 s12, v255, 15
	s_and_b64 s[6:7], s[0:1], vcc
	v_readlane_b32 s35, v255, 8
	v_readlane_b32 s49, v255, 10
	v_readlane_b32 s51, v255, 12
	v_readlane_b32 s53, v255, 14
	v_readlane_b32 s55, v252, 60
	v_readlane_b32 s57, v252, 62
	v_readlane_b32 s61, v253, 0
	v_readlane_b32 s63, v253, 2
	v_readlane_b32 s13, v255, 16
	v_readlane_b32 s58, v252, 28
	v_readlane_b32 s59, v252, 29
	s_mov_b64 exec, s[6:7]
	s_cbranch_execz .LBB0_905
	v_readlane_b32 s5, v255, 5
	s_waitcnt vmcnt(0) expcnt(0) lgkmcnt(0)
	s_nop 0
	v_mov_b32_e32 v0, s5
	ds_read_b32 v2, v0
	v_readlane_b32 s5, v255, 6
	s_waitcnt lgkmcnt(0)
	v_cmp_ne_u32_e32 vcc, 0, v2
	v_mov_b32_e32 v0, s5
	ds_read_b32 v0, v0
	s_cbranch_vccnz .LBB0_869
	s_mov_b32 s5, 1
	s_branch .LBB0_857
